# sample_part tile rewritten by hand: V rows as 16 dwordx4 loads all in flight with K, DPP/permlane reductions, packed f32 PV folded through LDS; page-table row requested with the selection mask
# speedup vs baseline: 1.0730x; 1.0044x over previous
; #define AIN(i) ld_ptr(c.la + 2 * (i))
; __device__ __forceinline__ void sample_part(const Ctx& c, int l, int it, LAS float* wl, int lane) {
;     ...
;         const unsigned long long* mp = (const unsigned long long*)(AWS + WS_SMASK) + bn; unsigned long long mask = *mp;
;         mask = ((unsigned long long)(unsigned)__builtin_amdgcn_readfirstlane((int)(unsigned)(mask >> 32)) << 32) | (unsigned)__builtin_amdgcn_readfirstlane((int)(unsigned)mask);
;         for (int k = 0; k < p; ++k) mask &= mask - 1;
;         if (mask) { const int j = __builtin_ctzll(mask);
;             if (j < 32) { const int page = __builtin_amdgcn_readfirstlane(((const int*)AIN(I_PTAB))[b * NPG + (j >> 1)]);
.LBB0_1381:
	ds_read_b32 v5, v1 offset:464
	ds_read_b32 v6, v1 offset:468
	s_and_b32 s2, 0xffff, s27
	s_lshl_b32 s2, s2, 3
	s_waitcnt lgkmcnt(1)
	v_readfirstlane_b32 s3, v5
	s_waitcnt lgkmcnt(0)
	v_readfirstlane_b32 s8, v6
	s_add_u32 s2, s3, s2
	s_addc_u32 s3, s8, 0
	ds_read_b32 v14, v1 offset:312
	ds_read_b32 v15, v1 offset:316
	v_mov_b32_e32 v5, 0x42f00000
	global_load_dwordx2 v[6:7], v5, s[2:3]
	s_lshl_b32 s10, s22, 6
	s_waitcnt lgkmcnt(0)
	v_readfirstlane_b32 s8, v14
	v_readfirstlane_b32 s9, v15
	v_and_b32_e32 v14, 15, v58
	v_lshl_add_u32 v14, v14, 2, s10
	s_nop 4
	global_load_dword v202, v14, s[8:9]
	s_cmp_eq_u32 s28, 0
	s_waitcnt vmcnt(0)
	v_readfirstlane_b32 s9, v7
	v_readfirstlane_b32 s8, v6
	s_cbranch_scc1 .LBB0_1383

; #define AIN(i) ld_ptr(c.la + 2 * (i))
; __device__ __forceinline__ void sample_part(const Ctx& c, int l, int it, LAS float* wl, int lane) {
;     ...
;         if (mask) { const int j = __builtin_ctzll(mask);
;             if (j < 32) { const int page = __builtin_amdgcn_readfirstlane(((const int*)AIN(I_PTAB))[b * NPG + (j >> 1)]);
;                 kbase = (const float*)AIN(I_CACHE) + (size_t)l * NPOOL * 128 * 512 + ((size_t)page * 128 + (j & 1) * 64) * 512 + 256 + n * 64; stride = 512; d0 = (float)(PASTL - j * 64); mode = 1; }
.LBB0_1386:
	s_andn2_b64 vcc, exec, s[2:3]
	s_cbranch_vccnz .LBB0_1390
	ds_read_b32 v5, v1 offset:312
	s_lshl_b32 s2, s22, 4
	s_lshr_b32 s3, s13, 1
	s_or_b32 s30, s3, s2
	s_lshl_b64 s[2:3], s[30:31], 2
	s_waitcnt lgkmcnt(0)
	v_readfirstlane_b32 s8, v5
	ds_read_b32 v5, v1 offset:316
	s_add_u32 s2, s8, s2
	v_readlane_b32 s10, v255, 6
	v_readlane_b32 s11, v255, 7
	s_mov_b32 s19, 1
	s_waitcnt lgkmcnt(0)
	v_readfirstlane_b32 s9, v5
	s_addc_u32 s3, s9, s3
	s_lshr_b32 s2, s13, 1
	s_nop 0
	v_readlane_b32 s2, v202, s2
	ds_read_b32 v5, v1 offset:272
	s_waitcnt lgkmcnt(0)
	v_readfirstlane_b32 s3, v5
	ds_read_b32 v5, v1 offset:276
	s_add_u32 s9, s3, s10
	s_waitcnt lgkmcnt(0)
	v_readfirstlane_b32 s8, v5
	s_addc_u32 s8, s8, s11
	s_ashr_i32 s3, s2, 31
	s_lshl_b64 s[2:3], s[2:3], 18
	s_add_u32 s2, s9, s2
	s_addc_u32 s3, s8, s3
	s_lshl_b32 s8, s13, 17
	s_and_b32 s8, s8, 0x20000
	s_add_u32 s2, s2, s8
	s_addc_u32 s3, s3, 0
	s_lshl_b32 s8, s20, 2
	s_add_u32 s2, s2, s8
	s_addc_u32 s3, s3, 0
	s_add_u32 s10, s2, 0x400
	s_addc_u32 s11, s3, 0
	s_lshl_b32 s2, s13, 6
	s_sub_i32 s2, 0x800, s2
	v_cvt_f32_u32_e32 v78, s2
	s_mov_b64 s[2:3], 0x200
	s_branch .LBB0_1389

; #define LAS __attribute__((address_space(3)))
; __device__ __forceinline__ void wave_lds_sync() { asm volatile("s_waitcnt lgkmcnt(0)" ::: "memory"); }
; __device__ __forceinline__ void sample_part(const Ctx& c, int l, int it, LAS float* wl, int lane) {
;     ...
;     if (mode == 1) {
;         const int kl = lane < nvalid ? lane : nvalid - 1;
;         const float* kp = kbase + (size_t)kl * stride;
;         f32x4 kr[16]; float vr[40], vs[24];
; #pragma unroll
;         for (int cch = 0; cch < 16; ++cch) kr[cch] = *(const f32x4*)(kp + 4 * cch);
; #pragma unroll
;         for (int j = 0; j < 40; ++j) vr[j] = __builtin_nontemporal_load(kbase + 128 + (size_t)(j < nvalid ? j : nvalid - 1) * stride + lane);
;         wave_lds_sync(); *(LAS f32x4*)(qbuf + lane * 4) = qv; wave_lds_sync();
;         float dot[4] = {0.f, 0.f, 0.f, 0.f};
; #pragma unroll
;         for (int cch = 0; cch < 16; ++cch) {
; #pragma unroll
;             for (int jj = 0; jj < 4; ++jj) { const f32x4 q0 = *(const LAS f32x4*)(qbuf + (cch * 4 + jj) * 4);
; #pragma unroll
;                 for (int g = 0; g < 4; ++g) dot[g] = fmaf(kr[cch][jj], q0[g], dot[g]); } }
.LBB0_1394:
	v_mov_b32_e32 v6, 1.0
	s_andn2_b64 vcc, exec, s[16:17]
	v_mov_b32_e32 v7, 1.0
	v_mov_b32_e32 v8, 1.0
	v_mov_b32_e32 v9, 1.0
	s_cbranch_vccnz .LBB0_1398
	s_cmp_lg_u32 s19, 1
	s_cbranch_scc1 .LBB0_1397
	s_add_i32 s8, s13, -1
	s_lshl_b32 s3, s2, 2
	s_lshl_b32 s9, s2, 4
	v_min_i32_e32 v0, s8, v58
	v_lshrrev_b32_e32 v14, 4, v58
	v_and_b32_e32 v15, 15, v58
	v_mul_lo_u32 v0, v0, s3
	v_mul_lo_u32 v20, v14, s3
	v_add_u32_e32 v21, 60, v14
	v_min_i32_e32 v21, s8, v21
	v_mul_lo_u32 v21, v21, s3
	v_lshl_add_u32 v20, v15, 4, v20
	v_lshl_add_u32 v21, v15, 4, v21
	s_mov_b64 s[16:17], s[10:11]
	global_load_dwordx4 v[80:83], v0, s[10:11] offset:0
	global_load_dwordx4 v[84:87], v0, s[10:11] offset:16
	global_load_dwordx4 v[88:91], v0, s[10:11] offset:32
	global_load_dwordx4 v[92:95], v0, s[10:11] offset:48
	global_load_dwordx4 v[96:99], v0, s[10:11] offset:64
	global_load_dwordx4 v[100:103], v0, s[10:11] offset:80
	global_load_dwordx4 v[104:107], v0, s[10:11] offset:96
	global_load_dwordx4 v[108:111], v0, s[10:11] offset:112
	global_load_dwordx4 v[112:115], v0, s[10:11] offset:128
	global_load_dwordx4 v[116:119], v0, s[10:11] offset:144
	global_load_dwordx4 v[120:123], v0, s[10:11] offset:160
	global_load_dwordx4 v[124:127], v0, s[10:11] offset:176
	global_load_dwordx4 v[128:131], v0, s[10:11] offset:192
	global_load_dwordx4 v[132:135], v0, s[10:11] offset:208
	global_load_dwordx4 v[136:139], v0, s[10:11] offset:224
	global_load_dwordx4 v[140:143], v0, s[10:11] offset:240
	global_load_dwordx4 v[24:27], v20, s[16:17] offset:512 nt
	s_add_u32 s16, s16, s9
	s_addc_u32 s17, s17, 0
	global_load_dwordx4 v[28:31], v20, s[16:17] offset:512 nt
	s_add_u32 s16, s16, s9
	s_addc_u32 s17, s17, 0
	global_load_dwordx4 v[32:35], v20, s[16:17] offset:512 nt
	s_add_u32 s16, s16, s9
	s_addc_u32 s17, s17, 0
	global_load_dwordx4 v[36:39], v20, s[16:17] offset:512 nt
	s_add_u32 s16, s16, s9
	s_addc_u32 s17, s17, 0
	global_load_dwordx4 v[40:43], v20, s[16:17] offset:512 nt
	s_add_u32 s16, s16, s9
	s_addc_u32 s17, s17, 0
	global_load_dwordx4 v[44:47], v20, s[16:17] offset:512 nt
	s_add_u32 s16, s16, s9
	s_addc_u32 s17, s17, 0
	global_load_dwordx4 v[48:51], v20, s[16:17] offset:512 nt
	s_add_u32 s16, s16, s9
	s_addc_u32 s17, s17, 0
	global_load_dwordx4 v[52:55], v20, s[16:17] offset:512 nt
	s_add_u32 s16, s16, s9
	s_addc_u32 s17, s17, 0
	global_load_dwordx4 v[144:147], v20, s[16:17] offset:512 nt
	s_add_u32 s16, s16, s9
	s_addc_u32 s17, s17, 0
	global_load_dwordx4 v[148:151], v20, s[16:17] offset:512 nt
	s_add_u32 s16, s16, s9
	s_addc_u32 s17, s17, 0
	global_load_dwordx4 v[152:155], v20, s[16:17] offset:512 nt
	s_add_u32 s16, s16, s9
	s_addc_u32 s17, s17, 0
	global_load_dwordx4 v[156:159], v20, s[16:17] offset:512 nt
	s_add_u32 s16, s16, s9
	s_addc_u32 s17, s17, 0
	global_load_dwordx4 v[160:163], v20, s[16:17] offset:512 nt
	s_add_u32 s16, s16, s9
	s_addc_u32 s17, s17, 0
	global_load_dwordx4 v[164:167], v20, s[16:17] offset:512 nt
	s_add_u32 s16, s16, s9
	s_addc_u32 s17, s17, 0
	global_load_dwordx4 v[168:171], v20, s[16:17] offset:512 nt
	global_load_dwordx4 v[60:63], v21, s[10:11] offset:512 nt
	v_cmp_gt_i32_e32 vcc, s13, v58
	s_lshl_b32 s2, s18, 2
	s_sub_i32 s2, 0x7e, s2
	s_lshl_b32 s2, s2, 23
	v_mov_b32_e32 v16, s2
	s_sub_i32 s2, s2, 0x800000
	v_mov_b32_e32 v17, s2
	s_sub_i32 s2, s2, 0x800000
	v_mov_b32_e32 v18, s2
	s_sub_i32 s2, s2, 0x800000
	v_mov_b32_e32 v19, s2
	v_cvt_f32_i32_e32 v14, v58
	v_lshl_add_u32 v76, v58, 4, s1
	v_mov_b32_e32 v77, s1
	v_sub_f32_e32 v14, v78, v14
	ds_write_b128 v76, v[10:13] offset:1024
	v_mul_f32_e32 v16, v16, v14
	v_mul_f32_e32 v17, v17, v14
	v_mul_f32_e32 v18, v18, v14
	v_mul_f32_e32 v19, v19, v14
	s_waitcnt lgkmcnt(0)
	ds_read_b128 v[68:71], v77 offset:1024
	ds_read_b128 v[72:75], v77 offset:1040
	ds_read_b128 v[2:5], v77 offset:1056
	ds_read_b128 v[6:9], v77 offset:1072
	s_waitcnt vmcnt(31) lgkmcnt(3)
	v_mul_f32_e32 v64, v80, v68
	v_mul_f32_e32 v65, v80, v69
	v_mul_f32_e32 v66, v80, v70
	v_mul_f32_e32 v67, v80, v71
	ds_read_b128 v[68:71], v77 offset:1088
	s_waitcnt lgkmcnt(3)
	v_fmac_f32_e32 v64, v81, v72
	v_fmac_f32_e32 v65, v81, v73
	v_fmac_f32_e32 v66, v81, v74
	v_fmac_f32_e32 v67, v81, v75
	ds_read_b128 v[72:75], v77 offset:1104
	s_waitcnt lgkmcnt(3)
	v_fmac_f32_e32 v64, v82, v2
	v_fmac_f32_e32 v65, v82, v3
	v_fmac_f32_e32 v66, v82, v4
	v_fmac_f32_e32 v67, v82, v5
	ds_read_b128 v[2:5], v77 offset:1120
	s_waitcnt lgkmcnt(3)
	v_fmac_f32_e32 v64, v83, v6
	v_fmac_f32_e32 v65, v83, v7
	v_fmac_f32_e32 v66, v83, v8
	v_fmac_f32_e32 v67, v83, v9
	ds_read_b128 v[6:9], v77 offset:1136
	s_waitcnt vmcnt(30) lgkmcnt(3)
	v_fmac_f32_e32 v64, v84, v68
	v_fmac_f32_e32 v65, v84, v69
	v_fmac_f32_e32 v66, v84, v70
	v_fmac_f32_e32 v67, v84, v71
	ds_read_b128 v[68:71], v77 offset:1152
	s_waitcnt lgkmcnt(3)
	v_fmac_f32_e32 v64, v85, v72
	v_fmac_f32_e32 v65, v85, v73
	v_fmac_f32_e32 v66, v85, v74
	v_fmac_f32_e32 v67, v85, v75
	ds_read_b128 v[72:75], v77 offset:1168
	s_waitcnt lgkmcnt(3)
	v_fmac_f32_e32 v64, v86, v2
	v_fmac_f32_e32 v65, v86, v3
	v_fmac_f32_e32 v66, v86, v4
	v_fmac_f32_e32 v67, v86, v5
	ds_read_b128 v[2:5], v77 offset:1184
	s_waitcnt lgkmcnt(3)
	v_fmac_f32_e32 v64, v87, v6
	v_fmac_f32_e32 v65, v87, v7
	v_fmac_f32_e32 v66, v87, v8
	v_fmac_f32_e32 v67, v87, v9
	ds_read_b128 v[6:9], v77 offset:1200
	s_waitcnt vmcnt(29) lgkmcnt(3)
	v_fmac_f32_e32 v64, v88, v68
	v_fmac_f32_e32 v65, v88, v69
	v_fmac_f32_e32 v66, v88, v70
	v_fmac_f32_e32 v67, v88, v71
	ds_read_b128 v[68:71], v77 offset:1216
	s_waitcnt lgkmcnt(3)
	v_fmac_f32_e32 v64, v89, v72
	v_fmac_f32_e32 v65, v89, v73
	v_fmac_f32_e32 v66, v89, v74
	v_fmac_f32_e32 v67, v89, v75
	ds_read_b128 v[72:75], v77 offset:1232
	s_waitcnt lgkmcnt(3)
; #define LAS __attribute__((address_space(3)))
; __device__ __forceinline__ void wave_lds_sync() { asm volatile("s_waitcnt lgkmcnt(0)" ::: "memory"); }
; __device__ __forceinline__ void sample_part(const Ctx& c, int l, int it, LAS float* wl, int lane) {
;     ...
;         wave_lds_sync(); *(LAS f32x4*)(qbuf + lane * 4) = qv; wave_lds_sync();
;         float dot[4] = {0.f, 0.f, 0.f, 0.f};
; #pragma unroll
;         for (int cch = 0; cch < 16; ++cch) {
; #pragma unroll
;             for (int jj = 0; jj < 4; ++jj) { const f32x4 q0 = *(const LAS f32x4*)(qbuf + (cch * 4 + jj) * 4);
; #pragma unroll
;                 for (int g = 0; g < 4; ++g) dot[g] = fmaf(kr[cch][jj], q0[g], dot[g]); } }
	v_fmac_f32_e32 v64, v90, v2
	v_fmac_f32_e32 v65, v90, v3
	v_fmac_f32_e32 v66, v90, v4
	v_fmac_f32_e32 v67, v90, v5
	ds_read_b128 v[2:5], v77 offset:1248
	s_waitcnt lgkmcnt(3)
	v_fmac_f32_e32 v64, v91, v6
	v_fmac_f32_e32 v65, v91, v7
	v_fmac_f32_e32 v66, v91, v8
	v_fmac_f32_e32 v67, v91, v9
	ds_read_b128 v[6:9], v77 offset:1264
	s_waitcnt vmcnt(28) lgkmcnt(3)
	v_fmac_f32_e32 v64, v92, v68
	v_fmac_f32_e32 v65, v92, v69
	v_fmac_f32_e32 v66, v92, v70
	v_fmac_f32_e32 v67, v92, v71
	ds_read_b128 v[68:71], v77 offset:1280
	s_waitcnt lgkmcnt(3)
	v_fmac_f32_e32 v64, v93, v72
	v_fmac_f32_e32 v65, v93, v73
	v_fmac_f32_e32 v66, v93, v74
	v_fmac_f32_e32 v67, v93, v75
	ds_read_b128 v[72:75], v77 offset:1296
	s_waitcnt lgkmcnt(3)
	v_fmac_f32_e32 v64, v94, v2
	v_fmac_f32_e32 v65, v94, v3
	v_fmac_f32_e32 v66, v94, v4
	v_fmac_f32_e32 v67, v94, v5
	ds_read_b128 v[2:5], v77 offset:1312
	s_waitcnt lgkmcnt(3)
	v_fmac_f32_e32 v64, v95, v6
	v_fmac_f32_e32 v65, v95, v7
	v_fmac_f32_e32 v66, v95, v8
	v_fmac_f32_e32 v67, v95, v9
	ds_read_b128 v[6:9], v77 offset:1328
	s_waitcnt vmcnt(27) lgkmcnt(3)
	v_fmac_f32_e32 v64, v96, v68
	v_fmac_f32_e32 v65, v96, v69
	v_fmac_f32_e32 v66, v96, v70
	v_fmac_f32_e32 v67, v96, v71
	ds_read_b128 v[68:71], v77 offset:1344
	s_waitcnt lgkmcnt(3)
	v_fmac_f32_e32 v64, v97, v72
	v_fmac_f32_e32 v65, v97, v73
	v_fmac_f32_e32 v66, v97, v74
	v_fmac_f32_e32 v67, v97, v75
	ds_read_b128 v[72:75], v77 offset:1360
	s_waitcnt lgkmcnt(3)
	v_fmac_f32_e32 v64, v98, v2
	v_fmac_f32_e32 v65, v98, v3
	v_fmac_f32_e32 v66, v98, v4
	v_fmac_f32_e32 v67, v98, v5
	ds_read_b128 v[2:5], v77 offset:1376
	s_waitcnt lgkmcnt(3)
	v_fmac_f32_e32 v64, v99, v6
	v_fmac_f32_e32 v65, v99, v7
	v_fmac_f32_e32 v66, v99, v8
	v_fmac_f32_e32 v67, v99, v9
	ds_read_b128 v[6:9], v77 offset:1392
	s_waitcnt vmcnt(26) lgkmcnt(3)
	v_fmac_f32_e32 v64, v100, v68
	v_fmac_f32_e32 v65, v100, v69
	v_fmac_f32_e32 v66, v100, v70
	v_fmac_f32_e32 v67, v100, v71
	ds_read_b128 v[68:71], v77 offset:1408
	s_waitcnt lgkmcnt(3)
	v_fmac_f32_e32 v64, v101, v72
	v_fmac_f32_e32 v65, v101, v73
	v_fmac_f32_e32 v66, v101, v74
	v_fmac_f32_e32 v67, v101, v75
	ds_read_b128 v[72:75], v77 offset:1424
	s_waitcnt lgkmcnt(3)
	v_fmac_f32_e32 v64, v102, v2
	v_fmac_f32_e32 v65, v102, v3
	v_fmac_f32_e32 v66, v102, v4
	v_fmac_f32_e32 v67, v102, v5
	ds_read_b128 v[2:5], v77 offset:1440
	s_waitcnt lgkmcnt(3)
	v_fmac_f32_e32 v64, v103, v6
	v_fmac_f32_e32 v65, v103, v7
	v_fmac_f32_e32 v66, v103, v8
	v_fmac_f32_e32 v67, v103, v9
	ds_read_b128 v[6:9], v77 offset:1456
	s_waitcnt vmcnt(25) lgkmcnt(3)
	v_fmac_f32_e32 v64, v104, v68
	v_fmac_f32_e32 v65, v104, v69
	v_fmac_f32_e32 v66, v104, v70
	v_fmac_f32_e32 v67, v104, v71
	ds_read_b128 v[68:71], v77 offset:1472
	s_waitcnt lgkmcnt(3)
	v_fmac_f32_e32 v64, v105, v72
	v_fmac_f32_e32 v65, v105, v73
	v_fmac_f32_e32 v66, v105, v74
	v_fmac_f32_e32 v67, v105, v75
	ds_read_b128 v[72:75], v77 offset:1488
	s_waitcnt lgkmcnt(3)
	v_fmac_f32_e32 v64, v106, v2
	v_fmac_f32_e32 v65, v106, v3
	v_fmac_f32_e32 v66, v106, v4
	v_fmac_f32_e32 v67, v106, v5
	ds_read_b128 v[2:5], v77 offset:1504
	s_waitcnt lgkmcnt(3)
	v_fmac_f32_e32 v64, v107, v6
	v_fmac_f32_e32 v65, v107, v7
	v_fmac_f32_e32 v66, v107, v8
	v_fmac_f32_e32 v67, v107, v9
	ds_read_b128 v[6:9], v77 offset:1520
	s_waitcnt vmcnt(24) lgkmcnt(3)
	v_fmac_f32_e32 v64, v108, v68
	v_fmac_f32_e32 v65, v108, v69
	v_fmac_f32_e32 v66, v108, v70
	v_fmac_f32_e32 v67, v108, v71
	ds_read_b128 v[68:71], v77 offset:1536
	s_waitcnt lgkmcnt(3)
	v_fmac_f32_e32 v64, v109, v72
	v_fmac_f32_e32 v65, v109, v73
	v_fmac_f32_e32 v66, v109, v74
	v_fmac_f32_e32 v67, v109, v75
	ds_read_b128 v[72:75], v77 offset:1552
	s_waitcnt lgkmcnt(3)
	v_fmac_f32_e32 v64, v110, v2
	v_fmac_f32_e32 v65, v110, v3
	v_fmac_f32_e32 v66, v110, v4
	v_fmac_f32_e32 v67, v110, v5
	ds_read_b128 v[2:5], v77 offset:1568
	s_waitcnt lgkmcnt(3)
	v_fmac_f32_e32 v64, v111, v6
	v_fmac_f32_e32 v65, v111, v7
	v_fmac_f32_e32 v66, v111, v8
	v_fmac_f32_e32 v67, v111, v9
	ds_read_b128 v[6:9], v77 offset:1584
	s_waitcnt vmcnt(23) lgkmcnt(3)
	v_fmac_f32_e32 v64, v112, v68
	v_fmac_f32_e32 v65, v112, v69
	v_fmac_f32_e32 v66, v112, v70
	v_fmac_f32_e32 v67, v112, v71
	ds_read_b128 v[68:71], v77 offset:1600
	s_waitcnt lgkmcnt(3)
	v_fmac_f32_e32 v64, v113, v72
	v_fmac_f32_e32 v65, v113, v73
	v_fmac_f32_e32 v66, v113, v74
	v_fmac_f32_e32 v67, v113, v75
	ds_read_b128 v[72:75], v77 offset:1616
	s_waitcnt lgkmcnt(3)
	v_fmac_f32_e32 v64, v114, v2
	v_fmac_f32_e32 v65, v114, v3
	v_fmac_f32_e32 v66, v114, v4
	v_fmac_f32_e32 v67, v114, v5
	ds_read_b128 v[2:5], v77 offset:1632
	s_waitcnt lgkmcnt(3)
	v_fmac_f32_e32 v64, v115, v6
	v_fmac_f32_e32 v65, v115, v7
	v_fmac_f32_e32 v66, v115, v8
	v_fmac_f32_e32 v67, v115, v9
	ds_read_b128 v[6:9], v77 offset:1648
	s_waitcnt vmcnt(22) lgkmcnt(3)
	v_fmac_f32_e32 v64, v116, v68
	v_fmac_f32_e32 v65, v116, v69
	v_fmac_f32_e32 v66, v116, v70
	v_fmac_f32_e32 v67, v116, v71
	ds_read_b128 v[68:71], v77 offset:1664
	s_waitcnt lgkmcnt(3)
	v_fmac_f32_e32 v64, v117, v72
	v_fmac_f32_e32 v65, v117, v73
	v_fmac_f32_e32 v66, v117, v74
	v_fmac_f32_e32 v67, v117, v75
	ds_read_b128 v[72:75], v77 offset:1680
	s_waitcnt lgkmcnt(3)
	v_fmac_f32_e32 v64, v118, v2
	v_fmac_f32_e32 v65, v118, v3
	v_fmac_f32_e32 v66, v118, v4
	v_fmac_f32_e32 v67, v118, v5
	ds_read_b128 v[2:5], v77 offset:1696
	s_waitcnt lgkmcnt(3)
	v_fmac_f32_e32 v64, v119, v6
	v_fmac_f32_e32 v65, v119, v7
	v_fmac_f32_e32 v66, v119, v8
	v_fmac_f32_e32 v67, v119, v9
	ds_read_b128 v[6:9], v77 offset:1712
	s_waitcnt vmcnt(21) lgkmcnt(3)
	v_fmac_f32_e32 v64, v120, v68
	v_fmac_f32_e32 v65, v120, v69
	v_fmac_f32_e32 v66, v120, v70
	v_fmac_f32_e32 v67, v120, v71
	ds_read_b128 v[68:71], v77 offset:1728
	s_waitcnt lgkmcnt(3)
; #define LAS __attribute__((address_space(3)))
; __device__ __forceinline__ void sample_part(const Ctx& c, int l, int it, LAS float* wl, int lane) {
;     ...
;         for (int cch = 0; cch < 16; ++cch) {
; #pragma unroll
;             for (int jj = 0; jj < 4; ++jj) { const f32x4 q0 = *(const LAS f32x4*)(qbuf + (cch * 4 + jj) * 4);
; #pragma unroll
;                 for (int g = 0; g < 4; ++g) dot[g] = fmaf(kr[cch][jj], q0[g], dot[g]); } }
;         __builtin_amdgcn_sched_barrier(0);
; #pragma unroll
;         for (int j = 0; j < 24; ++j) vs[j] = __builtin_nontemporal_load(kbase + 128 + (size_t)(40 + j < nvalid ? 40 + j : nvalid - 1) * stride + lane);
;         __builtin_amdgcn_sched_barrier(0);
;         const bool valid = lane < nvalid; const float dist = d0 - (float)lane;
;         f32x4 pr; float c8 = 0.125f; asm volatile("" : "+v"(c8));
; #pragma unroll
;         for (int g = 0; g < 4; ++g) { const float slope = exp2f(-(float)(n * 4 + g + 1)); const float sv = valid ? (dot[g] * c8 - slope * dist) : NEGV;
;             const float mx = wave_max(sv); const float pg = valid ? __expf(sv - mx) : 0.f; m4[g] = mx; l4[g] = wave_sum(pg); pr[g] = pg; }
	v_fmac_f32_e32 v64, v121, v72
	v_fmac_f32_e32 v65, v121, v73
	v_fmac_f32_e32 v66, v121, v74
	v_fmac_f32_e32 v67, v121, v75
	ds_read_b128 v[72:75], v77 offset:1744
	s_waitcnt lgkmcnt(3)
	v_fmac_f32_e32 v64, v122, v2
	v_fmac_f32_e32 v65, v122, v3
	v_fmac_f32_e32 v66, v122, v4
	v_fmac_f32_e32 v67, v122, v5
	ds_read_b128 v[2:5], v77 offset:1760
	s_waitcnt lgkmcnt(3)
	v_fmac_f32_e32 v64, v123, v6
	v_fmac_f32_e32 v65, v123, v7
	v_fmac_f32_e32 v66, v123, v8
	v_fmac_f32_e32 v67, v123, v9
	ds_read_b128 v[6:9], v77 offset:1776
	s_waitcnt vmcnt(20) lgkmcnt(3)
	v_fmac_f32_e32 v64, v124, v68
	v_fmac_f32_e32 v65, v124, v69
	v_fmac_f32_e32 v66, v124, v70
	v_fmac_f32_e32 v67, v124, v71
	ds_read_b128 v[68:71], v77 offset:1792
	s_waitcnt lgkmcnt(3)
	v_fmac_f32_e32 v64, v125, v72
	v_fmac_f32_e32 v65, v125, v73
	v_fmac_f32_e32 v66, v125, v74
	v_fmac_f32_e32 v67, v125, v75
	ds_read_b128 v[72:75], v77 offset:1808
	s_waitcnt lgkmcnt(3)
	v_fmac_f32_e32 v64, v126, v2
	v_fmac_f32_e32 v65, v126, v3
	v_fmac_f32_e32 v66, v126, v4
	v_fmac_f32_e32 v67, v126, v5
	ds_read_b128 v[2:5], v77 offset:1824
	s_waitcnt lgkmcnt(3)
	v_fmac_f32_e32 v64, v127, v6
	v_fmac_f32_e32 v65, v127, v7
	v_fmac_f32_e32 v66, v127, v8
	v_fmac_f32_e32 v67, v127, v9
	ds_read_b128 v[6:9], v77 offset:1840
	s_waitcnt vmcnt(19) lgkmcnt(3)
	v_fmac_f32_e32 v64, v128, v68
	v_fmac_f32_e32 v65, v128, v69
	v_fmac_f32_e32 v66, v128, v70
	v_fmac_f32_e32 v67, v128, v71
	ds_read_b128 v[68:71], v77 offset:1856
	s_waitcnt lgkmcnt(3)
	v_fmac_f32_e32 v64, v129, v72
	v_fmac_f32_e32 v65, v129, v73
	v_fmac_f32_e32 v66, v129, v74
	v_fmac_f32_e32 v67, v129, v75
	ds_read_b128 v[72:75], v77 offset:1872
	s_waitcnt lgkmcnt(3)
	v_fmac_f32_e32 v64, v130, v2
	v_fmac_f32_e32 v65, v130, v3
	v_fmac_f32_e32 v66, v130, v4
	v_fmac_f32_e32 v67, v130, v5
	ds_read_b128 v[2:5], v77 offset:1888
	s_waitcnt lgkmcnt(3)
	v_fmac_f32_e32 v64, v131, v6
	v_fmac_f32_e32 v65, v131, v7
	v_fmac_f32_e32 v66, v131, v8
	v_fmac_f32_e32 v67, v131, v9
	ds_read_b128 v[6:9], v77 offset:1904
	s_waitcnt vmcnt(18) lgkmcnt(3)
	v_fmac_f32_e32 v64, v132, v68
	v_fmac_f32_e32 v65, v132, v69
	v_fmac_f32_e32 v66, v132, v70
	v_fmac_f32_e32 v67, v132, v71
	ds_read_b128 v[68:71], v77 offset:1920
	s_waitcnt lgkmcnt(3)
	v_fmac_f32_e32 v64, v133, v72
	v_fmac_f32_e32 v65, v133, v73
	v_fmac_f32_e32 v66, v133, v74
	v_fmac_f32_e32 v67, v133, v75
	ds_read_b128 v[72:75], v77 offset:1936
	s_waitcnt lgkmcnt(3)
	v_fmac_f32_e32 v64, v134, v2
	v_fmac_f32_e32 v65, v134, v3
	v_fmac_f32_e32 v66, v134, v4
	v_fmac_f32_e32 v67, v134, v5
	ds_read_b128 v[2:5], v77 offset:1952
	s_waitcnt lgkmcnt(3)
	v_fmac_f32_e32 v64, v135, v6
	v_fmac_f32_e32 v65, v135, v7
	v_fmac_f32_e32 v66, v135, v8
	v_fmac_f32_e32 v67, v135, v9
	ds_read_b128 v[6:9], v77 offset:1968
	s_waitcnt vmcnt(17) lgkmcnt(3)
	v_fmac_f32_e32 v64, v136, v68
	v_fmac_f32_e32 v65, v136, v69
	v_fmac_f32_e32 v66, v136, v70
	v_fmac_f32_e32 v67, v136, v71
	ds_read_b128 v[68:71], v77 offset:1984
	s_waitcnt lgkmcnt(3)
	v_fmac_f32_e32 v64, v137, v72
	v_fmac_f32_e32 v65, v137, v73
	v_fmac_f32_e32 v66, v137, v74
	v_fmac_f32_e32 v67, v137, v75
	ds_read_b128 v[72:75], v77 offset:2000
	s_waitcnt lgkmcnt(3)
	v_fmac_f32_e32 v64, v138, v2
	v_fmac_f32_e32 v65, v138, v3
	v_fmac_f32_e32 v66, v138, v4
	v_fmac_f32_e32 v67, v138, v5
	ds_read_b128 v[2:5], v77 offset:2016
	s_waitcnt lgkmcnt(3)
	v_fmac_f32_e32 v64, v139, v6
	v_fmac_f32_e32 v65, v139, v7
	v_fmac_f32_e32 v66, v139, v8
	v_fmac_f32_e32 v67, v139, v9
	ds_read_b128 v[6:9], v77 offset:2032
	s_waitcnt vmcnt(16) lgkmcnt(3)
	v_fmac_f32_e32 v64, v140, v68
	v_fmac_f32_e32 v65, v140, v69
	v_fmac_f32_e32 v66, v140, v70
	v_fmac_f32_e32 v67, v140, v71
	s_waitcnt lgkmcnt(2)
	v_fmac_f32_e32 v64, v141, v72
	v_fmac_f32_e32 v65, v141, v73
	v_fmac_f32_e32 v66, v141, v74
	v_fmac_f32_e32 v67, v141, v75
	s_waitcnt lgkmcnt(1)
	v_fmac_f32_e32 v64, v142, v2
	v_fmac_f32_e32 v65, v142, v3
	v_fmac_f32_e32 v66, v142, v4
	v_fmac_f32_e32 v67, v142, v5
	s_waitcnt lgkmcnt(0)
	v_fmac_f32_e32 v64, v143, v6
	v_fmac_f32_e32 v65, v143, v7
	v_fmac_f32_e32 v66, v143, v8
	v_fmac_f32_e32 v67, v143, v9
	v_mul_f32_e32 v64, 0.125, v64
	v_mul_f32_e32 v65, 0.125, v65
	v_mul_f32_e32 v66, 0.125, v66
	v_mul_f32_e32 v67, 0.125, v67
	v_mov_b32_e32 v15, 0xf149f2ca
	v_sub_f32_e32 v64, v64, v16
	v_sub_f32_e32 v65, v65, v17
	v_sub_f32_e32 v66, v66, v18
	v_sub_f32_e32 v67, v67, v19
	v_cndmask_b32_e32 v64, v15, v64, vcc
	v_cndmask_b32_e32 v65, v15, v65, vcc
	v_cndmask_b32_e32 v66, v15, v66, vcc
	v_cndmask_b32_e32 v67, v15, v67, vcc
	v_mov_b32_e32 v2, v64
	v_mov_b32_e32 v3, v65
	v_mov_b32_e32 v4, v66
	v_mov_b32_e32 v5, v67
	s_nop 0
	v_max_f32_dpp v2, v2, v2 quad_perm:[1,0,3,2] row_mask:0xf bank_mask:0xf bound_ctrl:1
	v_max_f32_dpp v3, v3, v3 quad_perm:[1,0,3,2] row_mask:0xf bank_mask:0xf bound_ctrl:1
	v_max_f32_dpp v4, v4, v4 quad_perm:[1,0,3,2] row_mask:0xf bank_mask:0xf bound_ctrl:1
	v_max_f32_dpp v5, v5, v5 quad_perm:[1,0,3,2] row_mask:0xf bank_mask:0xf bound_ctrl:1
	v_max_f32_dpp v2, v2, v2 quad_perm:[2,3,0,1] row_mask:0xf bank_mask:0xf bound_ctrl:1
	v_max_f32_dpp v3, v3, v3 quad_perm:[2,3,0,1] row_mask:0xf bank_mask:0xf bound_ctrl:1
	v_max_f32_dpp v4, v4, v4 quad_perm:[2,3,0,1] row_mask:0xf bank_mask:0xf bound_ctrl:1
	v_max_f32_dpp v5, v5, v5 quad_perm:[2,3,0,1] row_mask:0xf bank_mask:0xf bound_ctrl:1
	v_max_f32_dpp v2, v2, v2 row_half_mirror row_mask:0xf bank_mask:0xf bound_ctrl:1
	v_max_f32_dpp v3, v3, v3 row_half_mirror row_mask:0xf bank_mask:0xf bound_ctrl:1
	v_max_f32_dpp v4, v4, v4 row_half_mirror row_mask:0xf bank_mask:0xf bound_ctrl:1
	v_max_f32_dpp v5, v5, v5 row_half_mirror row_mask:0xf bank_mask:0xf bound_ctrl:1
; #define LAS __attribute__((address_space(3)))
; __device__ __forceinline__ void wave_lds_sync() { asm volatile("s_waitcnt lgkmcnt(0)" ::: "memory"); }
; __device__ __forceinline__ void sample_part(const Ctx& c, int l, int it, LAS float* wl, int lane) {
;     ...
;         const bool valid = lane < nvalid; const float dist = d0 - (float)lane;
;         f32x4 pr; float c8 = 0.125f; asm volatile("" : "+v"(c8));
; #pragma unroll
;         for (int g = 0; g < 4; ++g) { const float slope = exp2f(-(float)(n * 4 + g + 1)); const float sv = valid ? (dot[g] * c8 - slope * dist) : NEGV;
;             const float mx = wave_max(sv); const float pg = valid ? __expf(sv - mx) : 0.f; m4[g] = mx; l4[g] = wave_sum(pg); pr[g] = pg; }
;         *(LAS f32x4*)(pbuf + lane * 4) = pr; wave_lds_sync();
; #pragma unroll
;         for (int j = 0; j < 40; ++j) { const f32x4 pj = *(const LAS f32x4*)(pbuf + j * 4);
; #pragma unroll
;             for (int g = 0; g < 4; ++g) asm("v_fmac_f32 %0, %1, %2" : "+v"(o4[g]) : "v"(pj[g]), "v"(vr[j])); }
; #pragma unroll
;         for (int j = 0; j < 24; ++j) { const f32x4 pj = *(const LAS f32x4*)(pbuf + (40 + j) * 4);
; #pragma unroll
;             for (int g = 0; g < 4; ++g) asm("v_fmac_f32 %0, %1, %2" : "+v"(o4[g]) : "v"(pj[g]), "v"(vs[j])); }
	v_max_f32_dpp v2, v2, v2 row_mirror row_mask:0xf bank_mask:0xf bound_ctrl:1
	v_max_f32_dpp v3, v3, v3 row_mirror row_mask:0xf bank_mask:0xf bound_ctrl:1
	v_max_f32_dpp v4, v4, v4 row_mirror row_mask:0xf bank_mask:0xf bound_ctrl:1
	v_max_f32_dpp v5, v5, v5 row_mirror row_mask:0xf bank_mask:0xf bound_ctrl:1
	v_mov_b32_e32 v20, v2
	v_mov_b32_e32 v21, v3
	v_mov_b32_e32 v22, v4
	v_mov_b32_e32 v23, v5
	v_permlane16_swap_b32_e32 v2, v20
	v_permlane16_swap_b32_e32 v3, v21
	v_permlane16_swap_b32_e32 v4, v22
	v_permlane16_swap_b32_e32 v5, v23
	v_max_f32_e32 v2, v2, v20
	v_max_f32_e32 v3, v3, v21
	v_max_f32_e32 v4, v4, v22
	v_max_f32_e32 v5, v5, v23
	v_mov_b32_e32 v20, v2
	v_mov_b32_e32 v21, v3
	v_mov_b32_e32 v22, v4
	v_mov_b32_e32 v23, v5
	v_permlane32_swap_b32_e32 v2, v20
	v_permlane32_swap_b32_e32 v3, v21
	v_permlane32_swap_b32_e32 v4, v22
	v_permlane32_swap_b32_e32 v5, v23
	v_max_f32_e32 v2, v2, v20
	v_max_f32_e32 v3, v3, v21
	v_max_f32_e32 v4, v4, v22
	v_max_f32_e32 v5, v5, v23
	v_sub_f32_e32 v64, v64, v2
	v_sub_f32_e32 v65, v65, v3
	v_sub_f32_e32 v66, v66, v4
	v_sub_f32_e32 v67, v67, v5
	v_mul_f32_e32 v64, 0x3fb8aa3b, v64
	v_mul_f32_e32 v65, 0x3fb8aa3b, v65
	v_mul_f32_e32 v66, 0x3fb8aa3b, v66
	v_mul_f32_e32 v67, 0x3fb8aa3b, v67
	v_exp_f32_e32 v64, v64
	v_exp_f32_e32 v65, v65
	v_exp_f32_e32 v66, v66
	v_exp_f32_e32 v67, v67
	v_cndmask_b32_e32 v96, 0, v64, vcc
	v_cndmask_b32_e32 v97, 0, v65, vcc
	v_cndmask_b32_e32 v98, 0, v66, vcc
	v_cndmask_b32_e32 v99, 0, v67, vcc
	ds_write_b128 v76, v[96:99] offset:2048
	v_mov_b32_e32 v6, v96
	v_mov_b32_e32 v7, v97
	v_mov_b32_e32 v8, v98
	v_mov_b32_e32 v9, v99
	v_lshrrev_b32_e32 v15, 4, v58
	v_lshl_add_u32 v15, v15, 4, s1
	v_add_f32_dpp v6, v6, v6 quad_perm:[1,0,3,2] row_mask:0xf bank_mask:0xf bound_ctrl:1
	v_add_f32_dpp v7, v7, v7 quad_perm:[1,0,3,2] row_mask:0xf bank_mask:0xf bound_ctrl:1
	v_add_f32_dpp v8, v8, v8 quad_perm:[1,0,3,2] row_mask:0xf bank_mask:0xf bound_ctrl:1
	v_add_f32_dpp v9, v9, v9 quad_perm:[1,0,3,2] row_mask:0xf bank_mask:0xf bound_ctrl:1
	v_add_f32_dpp v6, v6, v6 quad_perm:[2,3,0,1] row_mask:0xf bank_mask:0xf bound_ctrl:1
	v_add_f32_dpp v7, v7, v7 quad_perm:[2,3,0,1] row_mask:0xf bank_mask:0xf bound_ctrl:1
	v_add_f32_dpp v8, v8, v8 quad_perm:[2,3,0,1] row_mask:0xf bank_mask:0xf bound_ctrl:1
	v_add_f32_dpp v9, v9, v9 quad_perm:[2,3,0,1] row_mask:0xf bank_mask:0xf bound_ctrl:1
	v_add_f32_dpp v6, v6, v6 row_half_mirror row_mask:0xf bank_mask:0xf bound_ctrl:1
	v_add_f32_dpp v7, v7, v7 row_half_mirror row_mask:0xf bank_mask:0xf bound_ctrl:1
	v_add_f32_dpp v8, v8, v8 row_half_mirror row_mask:0xf bank_mask:0xf bound_ctrl:1
	v_add_f32_dpp v9, v9, v9 row_half_mirror row_mask:0xf bank_mask:0xf bound_ctrl:1
	v_add_f32_dpp v6, v6, v6 row_mirror row_mask:0xf bank_mask:0xf bound_ctrl:1
	v_add_f32_dpp v7, v7, v7 row_mirror row_mask:0xf bank_mask:0xf bound_ctrl:1
	v_add_f32_dpp v8, v8, v8 row_mirror row_mask:0xf bank_mask:0xf bound_ctrl:1
	v_add_f32_dpp v9, v9, v9 row_mirror row_mask:0xf bank_mask:0xf bound_ctrl:1
	v_mov_b32_e32 v20, v6
	v_mov_b32_e32 v21, v7
	v_mov_b32_e32 v22, v8
	v_mov_b32_e32 v23, v9
	v_permlane16_swap_b32_e32 v6, v20
	v_permlane16_swap_b32_e32 v7, v21
	v_permlane16_swap_b32_e32 v8, v22
	v_permlane16_swap_b32_e32 v9, v23
	v_add_f32_e32 v6, v6, v20
	v_add_f32_e32 v7, v7, v21
	v_add_f32_e32 v8, v8, v22
	v_add_f32_e32 v9, v9, v23
	v_mov_b32_e32 v20, v6
	v_mov_b32_e32 v21, v7
	v_mov_b32_e32 v22, v8
	v_mov_b32_e32 v23, v9
	v_permlane32_swap_b32_e32 v6, v20
	v_permlane32_swap_b32_e32 v7, v21
	v_permlane32_swap_b32_e32 v8, v22
	v_permlane32_swap_b32_e32 v9, v23
	v_add_f32_e32 v6, v6, v20
	v_add_f32_e32 v7, v7, v21
	v_add_f32_e32 v8, v8, v22
	v_add_f32_e32 v9, v9, v23
	v_mov_b32_e32 v80, 0
	v_mov_b32_e32 v81, 0
	v_mov_b32_e32 v82, 0
	v_mov_b32_e32 v83, 0
	v_mov_b32_e32 v84, 0
	v_mov_b32_e32 v85, 0
	v_mov_b32_e32 v86, 0
	v_mov_b32_e32 v87, 0
	v_mov_b32_e32 v88, 0
	v_mov_b32_e32 v89, 0
	v_mov_b32_e32 v90, 0
	v_mov_b32_e32 v91, 0
	v_mov_b32_e32 v92, 0
	v_mov_b32_e32 v93, 0
	v_mov_b32_e32 v94, 0
	v_mov_b32_e32 v95, 0
	s_waitcnt lgkmcnt(0)
	ds_read_b128 v[100:103], v15 offset:2048
	ds_read_b128 v[104:107], v15 offset:2112
	ds_read_b128 v[108:111], v15 offset:2176
	ds_read_b128 v[112:115], v15 offset:2240
	s_waitcnt vmcnt(15) lgkmcnt(3)
	v_pk_fma_f32 v[80:81], v[100:101], v[24:25], v[80:81] op_sel:[0,0,0] op_sel_hi:[0,1,1]
	v_pk_fma_f32 v[82:83], v[100:101], v[26:27], v[82:83] op_sel:[0,0,0] op_sel_hi:[0,1,1]
	v_pk_fma_f32 v[84:85], v[100:101], v[24:25], v[84:85] op_sel:[1,0,0] op_sel_hi:[1,1,1]
	v_pk_fma_f32 v[86:87], v[100:101], v[26:27], v[86:87] op_sel:[1,0,0] op_sel_hi:[1,1,1]
	v_pk_fma_f32 v[88:89], v[102:103], v[24:25], v[88:89] op_sel:[0,0,0] op_sel_hi:[0,1,1]
	v_pk_fma_f32 v[90:91], v[102:103], v[26:27], v[90:91] op_sel:[0,0,0] op_sel_hi:[0,1,1]
	v_pk_fma_f32 v[92:93], v[102:103], v[24:25], v[92:93] op_sel:[1,0,0] op_sel_hi:[1,1,1]
	v_pk_fma_f32 v[94:95], v[102:103], v[26:27], v[94:95] op_sel:[1,0,0] op_sel_hi:[1,1,1]
	ds_read_b128 v[100:103], v15 offset:2304
	s_waitcnt vmcnt(14) lgkmcnt(3)
	v_pk_fma_f32 v[80:81], v[104:105], v[28:29], v[80:81] op_sel:[0,0,0] op_sel_hi:[0,1,1]
	v_pk_fma_f32 v[82:83], v[104:105], v[30:31], v[82:83] op_sel:[0,0,0] op_sel_hi:[0,1,1]
	v_pk_fma_f32 v[84:85], v[104:105], v[28:29], v[84:85] op_sel:[1,0,0] op_sel_hi:[1,1,1]
	v_pk_fma_f32 v[86:87], v[104:105], v[30:31], v[86:87] op_sel:[1,0,0] op_sel_hi:[1,1,1]
	v_pk_fma_f32 v[88:89], v[106:107], v[28:29], v[88:89] op_sel:[0,0,0] op_sel_hi:[0,1,1]
	v_pk_fma_f32 v[90:91], v[106:107], v[30:31], v[90:91] op_sel:[0,0,0] op_sel_hi:[0,1,1]
	v_pk_fma_f32 v[92:93], v[106:107], v[28:29], v[92:93] op_sel:[1,0,0] op_sel_hi:[1,1,1]
	v_pk_fma_f32 v[94:95], v[106:107], v[30:31], v[94:95] op_sel:[1,0,0] op_sel_hi:[1,1,1]
	ds_read_b128 v[104:107], v15 offset:2368
	s_waitcnt vmcnt(13) lgkmcnt(3)
; #define LAS __attribute__((address_space(3)))
; __device__ __forceinline__ void wave_lds_sync() { asm volatile("s_waitcnt lgkmcnt(0)" ::: "memory"); }
; __device__ __forceinline__ void sample_part(const Ctx& c, int l, int it, LAS float* wl, int lane) {
;     ...
;         *(LAS f32x4*)(pbuf + lane * 4) = pr; wave_lds_sync();
; #pragma unroll
;         for (int j = 0; j < 40; ++j) { const f32x4 pj = *(const LAS f32x4*)(pbuf + j * 4);
; #pragma unroll
;             for (int g = 0; g < 4; ++g) asm("v_fmac_f32 %0, %1, %2" : "+v"(o4[g]) : "v"(pj[g]), "v"(vr[j])); }
; #pragma unroll
;         for (int j = 0; j < 24; ++j) { const f32x4 pj = *(const LAS f32x4*)(pbuf + (40 + j) * 4);
; #pragma unroll
;             for (int g = 0; g < 4; ++g) asm("v_fmac_f32 %0, %1, %2" : "+v"(o4[g]) : "v"(pj[g]), "v"(vs[j])); }
	v_pk_fma_f32 v[80:81], v[108:109], v[32:33], v[80:81] op_sel:[0,0,0] op_sel_hi:[0,1,1]
	v_pk_fma_f32 v[82:83], v[108:109], v[34:35], v[82:83] op_sel:[0,0,0] op_sel_hi:[0,1,1]
	v_pk_fma_f32 v[84:85], v[108:109], v[32:33], v[84:85] op_sel:[1,0,0] op_sel_hi:[1,1,1]
	v_pk_fma_f32 v[86:87], v[108:109], v[34:35], v[86:87] op_sel:[1,0,0] op_sel_hi:[1,1,1]
	v_pk_fma_f32 v[88:89], v[110:111], v[32:33], v[88:89] op_sel:[0,0,0] op_sel_hi:[0,1,1]
	v_pk_fma_f32 v[90:91], v[110:111], v[34:35], v[90:91] op_sel:[0,0,0] op_sel_hi:[0,1,1]
	v_pk_fma_f32 v[92:93], v[110:111], v[32:33], v[92:93] op_sel:[1,0,0] op_sel_hi:[1,1,1]
	v_pk_fma_f32 v[94:95], v[110:111], v[34:35], v[94:95] op_sel:[1,0,0] op_sel_hi:[1,1,1]
	ds_read_b128 v[108:111], v15 offset:2432
	s_waitcnt vmcnt(12) lgkmcnt(3)
	v_pk_fma_f32 v[80:81], v[112:113], v[36:37], v[80:81] op_sel:[0,0,0] op_sel_hi:[0,1,1]
	v_pk_fma_f32 v[82:83], v[112:113], v[38:39], v[82:83] op_sel:[0,0,0] op_sel_hi:[0,1,1]
	v_pk_fma_f32 v[84:85], v[112:113], v[36:37], v[84:85] op_sel:[1,0,0] op_sel_hi:[1,1,1]
	v_pk_fma_f32 v[86:87], v[112:113], v[38:39], v[86:87] op_sel:[1,0,0] op_sel_hi:[1,1,1]
	v_pk_fma_f32 v[88:89], v[114:115], v[36:37], v[88:89] op_sel:[0,0,0] op_sel_hi:[0,1,1]
	v_pk_fma_f32 v[90:91], v[114:115], v[38:39], v[90:91] op_sel:[0,0,0] op_sel_hi:[0,1,1]
	v_pk_fma_f32 v[92:93], v[114:115], v[36:37], v[92:93] op_sel:[1,0,0] op_sel_hi:[1,1,1]
	v_pk_fma_f32 v[94:95], v[114:115], v[38:39], v[94:95] op_sel:[1,0,0] op_sel_hi:[1,1,1]
	ds_read_b128 v[112:115], v15 offset:2496
	s_waitcnt vmcnt(11) lgkmcnt(3)
	v_pk_fma_f32 v[80:81], v[100:101], v[40:41], v[80:81] op_sel:[0,0,0] op_sel_hi:[0,1,1]
	v_pk_fma_f32 v[82:83], v[100:101], v[42:43], v[82:83] op_sel:[0,0,0] op_sel_hi:[0,1,1]
	v_pk_fma_f32 v[84:85], v[100:101], v[40:41], v[84:85] op_sel:[1,0,0] op_sel_hi:[1,1,1]
	v_pk_fma_f32 v[86:87], v[100:101], v[42:43], v[86:87] op_sel:[1,0,0] op_sel_hi:[1,1,1]
	v_pk_fma_f32 v[88:89], v[102:103], v[40:41], v[88:89] op_sel:[0,0,0] op_sel_hi:[0,1,1]
	v_pk_fma_f32 v[90:91], v[102:103], v[42:43], v[90:91] op_sel:[0,0,0] op_sel_hi:[0,1,1]
	v_pk_fma_f32 v[92:93], v[102:103], v[40:41], v[92:93] op_sel:[1,0,0] op_sel_hi:[1,1,1]
	v_pk_fma_f32 v[94:95], v[102:103], v[42:43], v[94:95] op_sel:[1,0,0] op_sel_hi:[1,1,1]
	ds_read_b128 v[100:103], v15 offset:2560
	s_waitcnt vmcnt(10) lgkmcnt(3)
	v_pk_fma_f32 v[80:81], v[104:105], v[44:45], v[80:81] op_sel:[0,0,0] op_sel_hi:[0,1,1]
	v_pk_fma_f32 v[82:83], v[104:105], v[46:47], v[82:83] op_sel:[0,0,0] op_sel_hi:[0,1,1]
	v_pk_fma_f32 v[84:85], v[104:105], v[44:45], v[84:85] op_sel:[1,0,0] op_sel_hi:[1,1,1]
	v_pk_fma_f32 v[86:87], v[104:105], v[46:47], v[86:87] op_sel:[1,0,0] op_sel_hi:[1,1,1]
	v_pk_fma_f32 v[88:89], v[106:107], v[44:45], v[88:89] op_sel:[0,0,0] op_sel_hi:[0,1,1]
	v_pk_fma_f32 v[90:91], v[106:107], v[46:47], v[90:91] op_sel:[0,0,0] op_sel_hi:[0,1,1]
	v_pk_fma_f32 v[92:93], v[106:107], v[44:45], v[92:93] op_sel:[1,0,0] op_sel_hi:[1,1,1]
	v_pk_fma_f32 v[94:95], v[106:107], v[46:47], v[94:95] op_sel:[1,0,0] op_sel_hi:[1,1,1]
	ds_read_b128 v[104:107], v15 offset:2624
	s_waitcnt vmcnt(9) lgkmcnt(3)
	v_pk_fma_f32 v[80:81], v[108:109], v[48:49], v[80:81] op_sel:[0,0,0] op_sel_hi:[0,1,1]
	v_pk_fma_f32 v[82:83], v[108:109], v[50:51], v[82:83] op_sel:[0,0,0] op_sel_hi:[0,1,1]
	v_pk_fma_f32 v[84:85], v[108:109], v[48:49], v[84:85] op_sel:[1,0,0] op_sel_hi:[1,1,1]
	v_pk_fma_f32 v[86:87], v[108:109], v[50:51], v[86:87] op_sel:[1,0,0] op_sel_hi:[1,1,1]
	v_pk_fma_f32 v[88:89], v[110:111], v[48:49], v[88:89] op_sel:[0,0,0] op_sel_hi:[0,1,1]
	v_pk_fma_f32 v[90:91], v[110:111], v[50:51], v[90:91] op_sel:[0,0,0] op_sel_hi:[0,1,1]
	v_pk_fma_f32 v[92:93], v[110:111], v[48:49], v[92:93] op_sel:[1,0,0] op_sel_hi:[1,1,1]
	v_pk_fma_f32 v[94:95], v[110:111], v[50:51], v[94:95] op_sel:[1,0,0] op_sel_hi:[1,1,1]
	ds_read_b128 v[108:111], v15 offset:2688
	s_waitcnt vmcnt(8) lgkmcnt(3)
	v_pk_fma_f32 v[80:81], v[112:113], v[52:53], v[80:81] op_sel:[0,0,0] op_sel_hi:[0,1,1]
	v_pk_fma_f32 v[82:83], v[112:113], v[54:55], v[82:83] op_sel:[0,0,0] op_sel_hi:[0,1,1]
	v_pk_fma_f32 v[84:85], v[112:113], v[52:53], v[84:85] op_sel:[1,0,0] op_sel_hi:[1,1,1]
	v_pk_fma_f32 v[86:87], v[112:113], v[54:55], v[86:87] op_sel:[1,0,0] op_sel_hi:[1,1,1]
	v_pk_fma_f32 v[88:89], v[114:115], v[52:53], v[88:89] op_sel:[0,0,0] op_sel_hi:[0,1,1]
	v_pk_fma_f32 v[90:91], v[114:115], v[54:55], v[90:91] op_sel:[0,0,0] op_sel_hi:[0,1,1]
	v_pk_fma_f32 v[92:93], v[114:115], v[52:53], v[92:93] op_sel:[1,0,0] op_sel_hi:[1,1,1]
	v_pk_fma_f32 v[94:95], v[114:115], v[54:55], v[94:95] op_sel:[1,0,0] op_sel_hi:[1,1,1]
	ds_read_b128 v[112:115], v15 offset:2752
	s_waitcnt vmcnt(7) lgkmcnt(3)
	v_pk_fma_f32 v[80:81], v[100:101], v[144:145], v[80:81] op_sel:[0,0,0] op_sel_hi:[0,1,1]
	v_pk_fma_f32 v[82:83], v[100:101], v[146:147], v[82:83] op_sel:[0,0,0] op_sel_hi:[0,1,1]
	v_pk_fma_f32 v[84:85], v[100:101], v[144:145], v[84:85] op_sel:[1,0,0] op_sel_hi:[1,1,1]
	v_pk_fma_f32 v[86:87], v[100:101], v[146:147], v[86:87] op_sel:[1,0,0] op_sel_hi:[1,1,1]
	v_pk_fma_f32 v[88:89], v[102:103], v[144:145], v[88:89] op_sel:[0,0,0] op_sel_hi:[0,1,1]
	v_pk_fma_f32 v[90:91], v[102:103], v[146:147], v[90:91] op_sel:[0,0,0] op_sel_hi:[0,1,1]
	v_pk_fma_f32 v[92:93], v[102:103], v[144:145], v[92:93] op_sel:[1,0,0] op_sel_hi:[1,1,1]
	v_pk_fma_f32 v[94:95], v[102:103], v[146:147], v[94:95] op_sel:[1,0,0] op_sel_hi:[1,1,1]
	ds_read_b128 v[100:103], v15 offset:2816
	s_waitcnt vmcnt(6) lgkmcnt(3)
; #define LAS __attribute__((address_space(3)))
; __device__ __forceinline__ float bf2f(bf16 v) { return __uint_as_float(((unsigned)v) << 16); }
; __device__ __forceinline__ void wave_lds_sync() { asm volatile("s_waitcnt lgkmcnt(0)" ::: "memory"); }
; __device__ __forceinline__ void sample_part(const Ctx& c, int l, int it, LAS float* wl, int lane) {
;     ...
;         *(LAS f32x4*)(pbuf + lane * 4) = pr; wave_lds_sync();
; #pragma unroll
;         for (int j = 0; j < 40; ++j) { const f32x4 pj = *(const LAS f32x4*)(pbuf + j * 4);
; #pragma unroll
;             for (int g = 0; g < 4; ++g) asm("v_fmac_f32 %0, %1, %2" : "+v"(o4[g]) : "v"(pj[g]), "v"(vr[j])); }
; #pragma unroll
;         for (int j = 0; j < 24; ++j) { const f32x4 pj = *(const LAS f32x4*)(pbuf + (40 + j) * 4);
; #pragma unroll
;             for (int g = 0; g < 4; ++g) asm("v_fmac_f32 %0, %1, %2" : "+v"(o4[g]) : "v"(pj[g]), "v"(vs[j])); }
;         wave_lds_sync();
;     } else if (mode == 2) {
;         const float kv = bf2f(kb1[lane]), vv = bf2f(kb1[128 + lane]);
;         float c8 = 0.125f; asm volatile("" : "+v"(c8));
; #pragma unroll
;         for (int g = 0; g < 4; ++g) { m4[g] = wave_sum(qv[g] * kv) * c8; l4[g] = 1.f; o4[g] = vv; }
;     }
;     float* pt = (float*)(AWS + WS_PART) + (size_t)it * 264;
;     if (lane == 0) { *(f32x4*)pt = (f32x4){m4[0], m4[1], m4[2], m4[3]}; *(f32x4*)(pt + 4) = (f32x4){l4[0], l4[1], l4[2], l4[3]}; }
; #pragma unroll
;     for (int g = 0; g < 4; ++g) pt[8 + g * 64 + lane] = o4[g];
	v_pk_fma_f32 v[80:81], v[104:105], v[148:149], v[80:81] op_sel:[0,0,0] op_sel_hi:[0,1,1]
	v_pk_fma_f32 v[82:83], v[104:105], v[150:151], v[82:83] op_sel:[0,0,0] op_sel_hi:[0,1,1]
	v_pk_fma_f32 v[84:85], v[104:105], v[148:149], v[84:85] op_sel:[1,0,0] op_sel_hi:[1,1,1]
	v_pk_fma_f32 v[86:87], v[104:105], v[150:151], v[86:87] op_sel:[1,0,0] op_sel_hi:[1,1,1]
	v_pk_fma_f32 v[88:89], v[106:107], v[148:149], v[88:89] op_sel:[0,0,0] op_sel_hi:[0,1,1]
	v_pk_fma_f32 v[90:91], v[106:107], v[150:151], v[90:91] op_sel:[0,0,0] op_sel_hi:[0,1,1]
	v_pk_fma_f32 v[92:93], v[106:107], v[148:149], v[92:93] op_sel:[1,0,0] op_sel_hi:[1,1,1]
	v_pk_fma_f32 v[94:95], v[106:107], v[150:151], v[94:95] op_sel:[1,0,0] op_sel_hi:[1,1,1]
	ds_read_b128 v[104:107], v15 offset:2880
	s_waitcnt vmcnt(5) lgkmcnt(3)
	v_pk_fma_f32 v[80:81], v[108:109], v[152:153], v[80:81] op_sel:[0,0,0] op_sel_hi:[0,1,1]
	v_pk_fma_f32 v[82:83], v[108:109], v[154:155], v[82:83] op_sel:[0,0,0] op_sel_hi:[0,1,1]
	v_pk_fma_f32 v[84:85], v[108:109], v[152:153], v[84:85] op_sel:[1,0,0] op_sel_hi:[1,1,1]
	v_pk_fma_f32 v[86:87], v[108:109], v[154:155], v[86:87] op_sel:[1,0,0] op_sel_hi:[1,1,1]
	v_pk_fma_f32 v[88:89], v[110:111], v[152:153], v[88:89] op_sel:[0,0,0] op_sel_hi:[0,1,1]
	v_pk_fma_f32 v[90:91], v[110:111], v[154:155], v[90:91] op_sel:[0,0,0] op_sel_hi:[0,1,1]
	v_pk_fma_f32 v[92:93], v[110:111], v[152:153], v[92:93] op_sel:[1,0,0] op_sel_hi:[1,1,1]
	v_pk_fma_f32 v[94:95], v[110:111], v[154:155], v[94:95] op_sel:[1,0,0] op_sel_hi:[1,1,1]
	ds_read_b128 v[108:111], v15 offset:2944
	s_waitcnt vmcnt(4) lgkmcnt(3)
	v_pk_fma_f32 v[80:81], v[112:113], v[156:157], v[80:81] op_sel:[0,0,0] op_sel_hi:[0,1,1]
	v_pk_fma_f32 v[82:83], v[112:113], v[158:159], v[82:83] op_sel:[0,0,0] op_sel_hi:[0,1,1]
	v_pk_fma_f32 v[84:85], v[112:113], v[156:157], v[84:85] op_sel:[1,0,0] op_sel_hi:[1,1,1]
	v_pk_fma_f32 v[86:87], v[112:113], v[158:159], v[86:87] op_sel:[1,0,0] op_sel_hi:[1,1,1]
	v_pk_fma_f32 v[88:89], v[114:115], v[156:157], v[88:89] op_sel:[0,0,0] op_sel_hi:[0,1,1]
	v_pk_fma_f32 v[90:91], v[114:115], v[158:159], v[90:91] op_sel:[0,0,0] op_sel_hi:[0,1,1]
	v_pk_fma_f32 v[92:93], v[114:115], v[156:157], v[92:93] op_sel:[1,0,0] op_sel_hi:[1,1,1]
	v_pk_fma_f32 v[94:95], v[114:115], v[158:159], v[94:95] op_sel:[1,0,0] op_sel_hi:[1,1,1]
	ds_read_b128 v[112:115], v15 offset:3008
	s_waitcnt vmcnt(3) lgkmcnt(3)
	v_pk_fma_f32 v[80:81], v[100:101], v[160:161], v[80:81] op_sel:[0,0,0] op_sel_hi:[0,1,1]
	v_pk_fma_f32 v[82:83], v[100:101], v[162:163], v[82:83] op_sel:[0,0,0] op_sel_hi:[0,1,1]
	v_pk_fma_f32 v[84:85], v[100:101], v[160:161], v[84:85] op_sel:[1,0,0] op_sel_hi:[1,1,1]
	v_pk_fma_f32 v[86:87], v[100:101], v[162:163], v[86:87] op_sel:[1,0,0] op_sel_hi:[1,1,1]
	v_pk_fma_f32 v[88:89], v[102:103], v[160:161], v[88:89] op_sel:[0,0,0] op_sel_hi:[0,1,1]
	v_pk_fma_f32 v[90:91], v[102:103], v[162:163], v[90:91] op_sel:[0,0,0] op_sel_hi:[0,1,1]
	v_pk_fma_f32 v[92:93], v[102:103], v[160:161], v[92:93] op_sel:[1,0,0] op_sel_hi:[1,1,1]
	v_pk_fma_f32 v[94:95], v[102:103], v[162:163], v[94:95] op_sel:[1,0,0] op_sel_hi:[1,1,1]
	s_waitcnt vmcnt(2) lgkmcnt(2)
	v_pk_fma_f32 v[80:81], v[104:105], v[164:165], v[80:81] op_sel:[0,0,0] op_sel_hi:[0,1,1]
	v_pk_fma_f32 v[82:83], v[104:105], v[166:167], v[82:83] op_sel:[0,0,0] op_sel_hi:[0,1,1]
	v_pk_fma_f32 v[84:85], v[104:105], v[164:165], v[84:85] op_sel:[1,0,0] op_sel_hi:[1,1,1]
	v_pk_fma_f32 v[86:87], v[104:105], v[166:167], v[86:87] op_sel:[1,0,0] op_sel_hi:[1,1,1]
	v_pk_fma_f32 v[88:89], v[106:107], v[164:165], v[88:89] op_sel:[0,0,0] op_sel_hi:[0,1,1]
	v_pk_fma_f32 v[90:91], v[106:107], v[166:167], v[90:91] op_sel:[0,0,0] op_sel_hi:[0,1,1]
	v_pk_fma_f32 v[92:93], v[106:107], v[164:165], v[92:93] op_sel:[1,0,0] op_sel_hi:[1,1,1]
	v_pk_fma_f32 v[94:95], v[106:107], v[166:167], v[94:95] op_sel:[1,0,0] op_sel_hi:[1,1,1]
	s_waitcnt vmcnt(1) lgkmcnt(1)
	v_pk_fma_f32 v[80:81], v[108:109], v[168:169], v[80:81] op_sel:[0,0,0] op_sel_hi:[0,1,1]
	v_pk_fma_f32 v[82:83], v[108:109], v[170:171], v[82:83] op_sel:[0,0,0] op_sel_hi:[0,1,1]
	v_pk_fma_f32 v[84:85], v[108:109], v[168:169], v[84:85] op_sel:[1,0,0] op_sel_hi:[1,1,1]
	v_pk_fma_f32 v[86:87], v[108:109], v[170:171], v[86:87] op_sel:[1,0,0] op_sel_hi:[1,1,1]
	v_pk_fma_f32 v[88:89], v[110:111], v[168:169], v[88:89] op_sel:[0,0,0] op_sel_hi:[0,1,1]
	v_pk_fma_f32 v[90:91], v[110:111], v[170:171], v[90:91] op_sel:[0,0,0] op_sel_hi:[0,1,1]
	v_pk_fma_f32 v[92:93], v[110:111], v[168:169], v[92:93] op_sel:[1,0,0] op_sel_hi:[1,1,1]
	v_pk_fma_f32 v[94:95], v[110:111], v[170:171], v[94:95] op_sel:[1,0,0] op_sel_hi:[1,1,1]
	s_waitcnt vmcnt(0) lgkmcnt(0)
	v_pk_fma_f32 v[80:81], v[112:113], v[60:61], v[80:81] op_sel:[0,0,0] op_sel_hi:[0,1,1]
	v_pk_fma_f32 v[82:83], v[112:113], v[62:63], v[82:83] op_sel:[0,0,0] op_sel_hi:[0,1,1]
	v_pk_fma_f32 v[84:85], v[112:113], v[60:61], v[84:85] op_sel:[1,0,0] op_sel_hi:[1,1,1]
	v_pk_fma_f32 v[86:87], v[112:113], v[62:63], v[86:87] op_sel:[1,0,0] op_sel_hi:[1,1,1]
	v_pk_fma_f32 v[88:89], v[114:115], v[60:61], v[88:89] op_sel:[0,0,0] op_sel_hi:[0,1,1]
	v_pk_fma_f32 v[90:91], v[114:115], v[62:63], v[90:91] op_sel:[0,0,0] op_sel_hi:[0,1,1]
	v_pk_fma_f32 v[92:93], v[114:115], v[60:61], v[92:93] op_sel:[1,0,0] op_sel_hi:[1,1,1]
	v_pk_fma_f32 v[94:95], v[114:115], v[62:63], v[94:95] op_sel:[1,0,0] op_sel_hi:[1,1,1]
	v_lshrrev_b32_e32 v0, 4, v58
	v_and_b32_e32 v15, 15, v58
	v_lshl_add_u32 v0, v0, 8, s1
	v_lshl_add_u32 v0, v15, 4, v0
	v_lshl_add_u32 v14, v58, 2, s1
	ds_write_b128 v0, v[80:83] offset:1024
	ds_write_b128 v0, v[84:87] offset:2048
	ds_write_b128 v0, v[88:91] offset:3072
	ds_write_b128 v0, v[92:95] offset:4096
	s_waitcnt lgkmcnt(0)
	ds_read2st64_b32 v[120:121], v14 offset0:4 offset1:5
	ds_read2st64_b32 v[122:123], v14 offset0:6 offset1:7
	ds_read2st64_b32 v[124:125], v14 offset0:8 offset1:9
	ds_read2st64_b32 v[126:127], v14 offset0:10 offset1:11
	ds_read2st64_b32 v[128:129], v14 offset0:12 offset1:13
	ds_read2st64_b32 v[130:131], v14 offset0:14 offset1:15
	ds_read2st64_b32 v[132:133], v14 offset0:16 offset1:17
	ds_read2st64_b32 v[134:135], v14 offset0:18 offset1:19
	s_waitcnt lgkmcnt(0)
	v_add_f32_e32 v120, v120, v121
	v_add_f32_e32 v124, v124, v125
	v_add_f32_e32 v128, v128, v129
	v_add_f32_e32 v132, v132, v133
	v_add_f32_e32 v122, v122, v123
	v_add_f32_e32 v126, v126, v127
	v_add_f32_e32 v130, v130, v131
	v_add_f32_e32 v134, v134, v135
	v_add_f32_e32 v22, v120, v122
	v_add_f32_e32 v21, v124, v126
	v_add_f32_e32 v20, v128, v130
	v_add_f32_e32 v14, v132, v134
	s_branch .LBB0_1398
